# adds: PL epilogue E loads one chunk ahead; non-leader workgroups poll the cross-XCC release word; bg conversion starts 2us after barrier entry
# speedup vs baseline: 1.0162x; 1.0076x over previous
.LBB0_434:
	v_lshl_add_u32 v192, s13, 8, v220
	v_ashrrev_i32_e32 v193, 31, v192
	v_lshlrev_b64 v[200:201], 6, v[192:193]
	v_lshl_add_u64 v[132:133], v[170:171], 0, v[200:201]
	global_load_dwordx4 v[132:135], v[132:133], off
	v_or_b32_e32 v190, 16, v192
	v_ashrrev_i32_e32 v191, 31, v190
	v_lshlrev_b64 v[202:203], 6, v[190:191]
	v_lshl_add_u64 v[136:137], v[170:171], 0, v[202:203]
	global_load_dwordx4 v[136:139], v[136:137], off
	v_or_b32_e32 v188, 32, v192
	v_ashrrev_i32_e32 v189, 31, v188
	v_lshlrev_b64 v[204:205], 6, v[188:189]
	v_lshl_add_u64 v[140:141], v[170:171], 0, v[204:205]
	global_load_dwordx4 v[140:143], v[140:141], off
	v_or_b32_e32 v186, 48, v192
	v_ashrrev_i32_e32 v187, 31, v186
	v_lshlrev_b64 v[206:207], 6, v[186:187]
	v_lshl_add_u64 v[144:145], v[170:171], 0, v[206:207]
	global_load_dwordx4 v[144:147], v[144:145], off
	v_add_u32_e32 v184, 0x80, v192
	v_ashrrev_i32_e32 v185, 31, v184
	v_lshlrev_b64 v[208:209], 6, v[184:185]
	v_lshl_add_u64 v[148:149], v[170:171], 0, v[208:209]
	global_load_dwordx4 v[148:151], v[148:149], off
	v_add_u32_e32 v182, 0x90, v192
	v_ashrrev_i32_e32 v183, 31, v182
	v_lshlrev_b64 v[210:211], 6, v[182:183]
	v_lshl_add_u64 v[152:153], v[170:171], 0, v[210:211]
	global_load_dwordx4 v[152:155], v[152:153], off
	v_add_u32_e32 v180, 0xa0, v192
	v_ashrrev_i32_e32 v181, 31, v180
	v_lshlrev_b64 v[212:213], 6, v[180:181]
	v_lshl_add_u64 v[156:157], v[170:171], 0, v[212:213]
	global_load_dwordx4 v[156:159], v[156:157], off
	v_add_u32_e32 v178, 0xb0, v192
	v_ashrrev_i32_e32 v179, 31, v178
	v_lshlrev_b64 v[214:215], 6, v[178:179]
	v_lshl_add_u64 v[160:161], v[170:171], 0, v[214:215]
	global_load_dwordx4 v[160:163], v[160:161], off
	v_xor_b32_e32 v232, 64, v224
	v_xor_b32_e32 v225, 0x80, v224
	v_lshl_or_b32 v198, s12, 8, v222
	v_ashrrev_i32_e32 v199, 31, v198
	v_lshlrev_b64 v[218:219], 11, v[192:193]
	v_lshl_add_u32 v228, v192, 10, v198
	v_lshlrev_b32_e32 v228, 1, v228
	global_load_dwordx4 v[164:167], v228, s[44:45]
	global_load_dwordx4 v[168:171], v228, s[44:45] offset:256
	v_lshl_add_u32 v228, v190, 10, v198
	v_lshlrev_b32_e32 v228, 1, v228
	global_load_dwordx4 v[174:177], v228, s[44:45]
	global_load_dwordx4 v[220:223], v228, s[44:45] offset:256
	s_and_b64 vcc, exec, s[28:29]
	s_waitcnt vmcnt(4)
	v_mov_b32_e32 v216, v133
	v_mov_b32_e32 v217, v134
	v_mov_b32_e32 v133, v135
	v_pk_add_f32 v[132:133], v[216:217], v[132:133]
	s_nop 0
	v_add_f32_e32 v132, v132, v133
	ds_bpermute_b32 v133, v232, v132
	s_waitcnt lgkmcnt(0)
	v_add_f32_e32 v132, v132, v133
	ds_bpermute_b32 v133, v225, v132
	s_waitcnt lgkmcnt(0)
	v_add_f32_e32 v132, v132, v133
	v_fmamk_f32 v132, v132, 0x3a800000, v226
	v_rsq_f32_e32 v216, v132
	v_add_f32_e32 v132, v136, v137
	v_add_f32_e32 v133, v138, v139
	v_add_f32_e32 v132, v132, v133
	ds_bpermute_b32 v133, v232, v132
	v_pk_mul_f32 v[128:129], v[128:129], v[216:217] op_sel_hi:[1,0]
	v_pk_mul_f32 v[130:131], v[130:131], v[216:217] op_sel_hi:[1,0]
	v_pk_mul_f32 v[128:129], v[128:129], s[14:15] op_sel_hi:[1,0]
	v_pk_mul_f32 v[130:131], v[130:131], s[14:15] op_sel_hi:[1,0]
	s_waitcnt lgkmcnt(0)
	v_add_f32_e32 v245, v132, v133
	v_add_f32_e32 v132, v140, v141
	v_add_f32_e32 v133, v142, v143
	v_add_f32_e32 v132, v132, v133
	ds_bpermute_b32 v133, v232, v132
	v_pk_mul_f32 v[124:125], v[124:125], v[216:217] op_sel_hi:[1,0]
	v_pk_mul_f32 v[126:127], v[126:127], v[216:217] op_sel_hi:[1,0]
	v_exp_f32_e32 v128, v128
	v_exp_f32_e32 v129, v129
	s_waitcnt lgkmcnt(0)
	v_add_f32_e32 v243, v132, v133
	v_add_f32_e32 v132, v144, v145
	v_add_f32_e32 v133, v146, v147
	v_add_f32_e32 v132, v132, v133
	ds_bpermute_b32 v133, v232, v132
	v_exp_f32_e32 v130, v130
	v_exp_f32_e32 v131, v131
	v_pk_mul_f32 v[126:127], v[126:127], s[14:15] op_sel_hi:[1,0]
	v_pk_mul_f32 v[124:125], v[124:125], s[14:15] op_sel_hi:[1,0]
	s_waitcnt lgkmcnt(0)
	v_add_f32_e32 v241, v132, v133
	v_add_f32_e32 v132, v148, v149
	v_add_f32_e32 v133, v150, v151
	v_add_f32_e32 v132, v132, v133
	ds_bpermute_b32 v133, v232, v132
	v_exp_f32_e32 v124, v124
	v_exp_f32_e32 v125, v125
	v_exp_f32_e32 v126, v126
	v_exp_f32_e32 v127, v127
	s_waitcnt lgkmcnt(0)
	v_add_f32_e32 v239, v132, v133
	v_add_f32_e32 v132, v152, v153
	v_add_f32_e32 v133, v154, v155
	v_add_f32_e32 v132, v132, v133
	ds_bpermute_b32 v133, v232, v132
	v_pk_add_f32 v[130:131], v[130:131], 1.0 op_sel_hi:[1,0]
	v_pk_add_f32 v[128:129], v[128:129], 1.0 op_sel_hi:[1,0]
	v_rcp_f32_e32 v130, v130
	v_rcp_f32_e32 v128, v128
	s_waitcnt lgkmcnt(0)
	v_add_f32_e32 v237, v132, v133
	v_add_f32_e32 v132, v156, v157
	v_add_f32_e32 v133, v158, v159
	v_add_f32_e32 v132, v132, v133
	ds_bpermute_b32 v133, v232, v132
	v_rcp_f32_e32 v129, v129
	v_rcp_f32_e32 v131, v131
	v_pk_add_f32 v[126:127], v[126:127], 1.0 op_sel_hi:[1,0]
	v_pk_add_f32 v[124:125], v[124:125], 1.0 op_sel_hi:[1,0]
	s_waitcnt lgkmcnt(0)
	v_add_f32_e32 v235, v132, v133
	v_add_f32_e32 v132, v160, v161
	v_add_f32_e32 v133, v162, v163
	v_add_f32_e32 v132, v132, v133
	ds_bpermute_b32 v133, v232, v132
	ds_bpermute_b32 v246, v225, v245
	ds_bpermute_b32 v244, v225, v243
	ds_bpermute_b32 v242, v225, v241
	ds_bpermute_b32 v240, v225, v239
	s_waitcnt lgkmcnt(4)
	v_add_f32_e32 v233, v132, v133
	v_lshlrev_b64 v[132:133], 10, v[192:193]
	v_lshl_add_u64 v[132:133], v[132:133], 0, v[198:199]
	v_lshlrev_b64 v[132:133], 1, v[132:133]
	v_lshl_add_u64 v[134:135], s[42:43], 0, v[132:133]
	global_load_dwordx4 v[156:159], v[134:135], off
	v_or_b32_e32 v132, 0x100, v132
	v_lshl_add_u64 v[134:135], s[42:43], 0, v[132:133]
	global_load_dwordx4 v[148:151], v[134:135], off
	v_lshlrev_b64 v[132:133], 10, v[190:191]
	v_lshl_add_u64 v[132:133], v[132:133], 0, v[198:199]
	v_lshlrev_b64 v[136:137], 1, v[132:133]
	v_lshl_add_u64 v[132:133], s[42:43], 0, v[136:137]
	global_load_dwordx4 v[140:143], v[132:133], off
	v_or_b32_e32 v136, 0x100, v136
	v_lshl_add_u64 v[132:133], s[42:43], 0, v[136:137]
	global_load_dwordx4 v[132:135], v[132:133], off
	ds_bpermute_b32 v238, v225, v237
	ds_bpermute_b32 v236, v225, v235
	s_waitcnt vmcnt(4)
	v_mov_b32_e32 v160, v164
	v_mov_b32_e32 v161, v165
	v_mov_b32_e32 v162, v166
	v_mov_b32_e32 v163, v167
	v_mov_b32_e32 v152, v168
	v_mov_b32_e32 v153, v169
	v_mov_b32_e32 v154, v170
	v_mov_b32_e32 v155, v171
	v_mov_b32_e32 v144, v174
	v_mov_b32_e32 v145, v175
	v_mov_b32_e32 v146, v176
	v_mov_b32_e32 v147, v177
	v_mov_b32_e32 v136, v220
	v_mov_b32_e32 v137, v221
	v_mov_b32_e32 v138, v222
	v_mov_b32_e32 v139, v223
	v_lshl_add_u32 v228, v188, 10, v198
	v_lshlrev_b32_e32 v228, 1, v228
	global_load_dwordx4 v[164:167], v228, s[44:45]
	global_load_dwordx4 v[168:171], v228, s[44:45] offset:256
	v_lshl_add_u32 v228, v186, 10, v198
	v_lshlrev_b32_e32 v228, 1, v228
	global_load_dwordx4 v[174:177], v228, s[44:45]
	global_load_dwordx4 v[220:223], v228, s[44:45] offset:256
	ds_bpermute_b32 v234, v225, v233
	v_rcp_f32_e32 v194, v124
	v_rcp_f32_e32 v195, v125
	v_rcp_f32_e32 v196, v126
	v_rcp_f32_e32 v197, v127
	s_waitcnt vmcnt(7)
	v_lshlrev_b32_e32 v126, 16, v156
	v_and_b32_e32 v127, 0xffff0000, v156
	v_lshlrev_b32_e32 v124, 16, v157
	s_waitcnt vmcnt(7)
	v_lshlrev_b32_e32 v248, 16, v160
	v_and_b32_e32 v249, 0xffff0000, v160
	v_lshlrev_b32_e32 v160, 16, v161
	v_and_b32_e32 v161, 0xffff0000, v161
	v_and_b32_e32 v125, 0xffff0000, v157
	v_lshlrev_b32_e32 v230, 16, v162
	v_and_b32_e32 v231, 0xffff0000, v162
	v_lshlrev_b32_e32 v162, 16, v163
	v_and_b32_e32 v163, 0xffff0000, v163
	v_pk_fma_f32 v[124:125], v[130:131], v[160:161], v[124:125]
	v_pk_fma_f32 v[126:127], v[128:129], v[248:249], v[126:127]
	v_lshlrev_b32_e32 v128, 16, v158
	v_and_b32_e32 v129, 0xffff0000, v158
	v_lshlrev_b32_e32 v130, 16, v159
	v_and_b32_e32 v131, 0xffff0000, v159
	v_lshl_add_u64 v[156:157], s[72:73], 0, v[218:219]
	v_pk_fma_f32 v[128:129], v[194:195], v[230:231], v[128:129]
	v_pk_fma_f32 v[130:131], v[196:197], v[162:163], v[130:131]
	v_lshl_add_u64 v[156:157], v[198:199], 1, v[156:157]
	s_cbranch_vccz .LBB0_436
	v_cvt_pk_bf16_f32 v158, v126, v127
	v_cvt_pk_bf16_f32 v159, v124, v125
	v_cvt_pk_bf16_f32 v160, v128, v129
	v_cvt_pk_bf16_f32 v161, v130, v131
	global_store_dwordx4 v[156:157], v[158:161], off
.LBB0_436:
	v_mov_b32_e32 v217, v216
	s_nop 0
	v_mov_b32_e32 v158, v216
	v_mov_b32_e32 v159, v216
	v_pk_mul_f32 v[122:123], v[122:123], v[158:159]
	v_pk_mul_f32 v[120:121], v[120:121], v[216:217]
	v_pk_mul_f32 v[122:123], v[122:123], s[14:15] op_sel_hi:[1,0]
	v_pk_mul_f32 v[120:121], v[120:121], s[14:15] op_sel_hi:[1,0]
	v_pk_mul_f32 v[118:119], v[118:119], v[158:159]
	v_pk_mul_f32 v[116:117], v[116:117], v[216:217]
	v_exp_f32_e32 v120, v120
	v_exp_f32_e32 v122, v122
	v_exp_f32_e32 v123, v123
	v_exp_f32_e32 v121, v121
	v_pk_mul_f32 v[118:119], v[118:119], s[14:15] op_sel_hi:[1,0]
	v_pk_mul_f32 v[116:117], v[116:117], s[14:15] op_sel_hi:[1,0]
	v_exp_f32_e32 v118, v118
	v_exp_f32_e32 v116, v116
	v_exp_f32_e32 v119, v119
	v_exp_f32_e32 v117, v117
	v_pk_add_f32 v[122:123], v[122:123], 1.0 op_sel_hi:[1,0]
	v_pk_add_f32 v[120:121], v[120:121], 1.0 op_sel_hi:[1,0]
	v_rcp_f32_e32 v122, v122
	v_rcp_f32_e32 v120, v120
	v_rcp_f32_e32 v121, v121
	v_rcp_f32_e32 v123, v123
	v_pk_add_f32 v[118:119], v[118:119], 1.0 op_sel_hi:[1,0]
	v_pk_add_f32 v[116:117], v[116:117], 1.0 op_sel_hi:[1,0]
	v_rcp_f32_e32 v118, v118
	v_rcp_f32_e32 v116, v116
	v_rcp_f32_e32 v117, v117
	v_rcp_f32_e32 v119, v119
	s_waitcnt vmcnt(6)
	v_lshlrev_b32_e32 v160, 16, v152
	v_and_b32_e32 v161, 0xffff0000, v152
	v_lshlrev_b32_e32 v152, 16, v153
	v_and_b32_e32 v153, 0xffff0000, v153
	v_lshlrev_b32_e32 v162, 16, v148
	v_and_b32_e32 v163, 0xffff0000, v148
	v_lshlrev_b32_e32 v148, 16, v149
	v_and_b32_e32 v149, 0xffff0000, v149
	v_lshlrev_b32_e32 v158, 16, v154
	v_and_b32_e32 v159, 0xffff0000, v154
	v_lshlrev_b32_e32 v154, 16, v155
	v_and_b32_e32 v155, 0xffff0000, v155
	v_pk_fma_f32 v[148:149], v[122:123], v[152:153], v[148:149]
	v_pk_fma_f32 v[152:153], v[120:121], v[160:161], v[162:163]
	v_lshlrev_b32_e32 v120, 16, v150
	v_and_b32_e32 v121, 0xffff0000, v150
	v_lshlrev_b32_e32 v122, 16, v151
	v_and_b32_e32 v123, 0xffff0000, v151
	v_pk_fma_f32 v[150:151], v[116:117], v[158:159], v[120:121]
	v_pk_fma_f32 v[154:155], v[118:119], v[154:155], v[122:123]
	s_and_b64 vcc, exec, s[28:29]
	s_cbranch_vccz .LBB0_438
	v_cvt_pk_bf16_f32 v116, v152, v153
	v_cvt_pk_bf16_f32 v117, v148, v149
	v_cvt_pk_bf16_f32 v118, v150, v151
	v_cvt_pk_bf16_f32 v119, v154, v155
	global_store_dwordx4 v[156:157], v[116:119], off offset:256

.LBB0_440:
	s_or_b64 exec, exec, s[4:5]
	v_add_f32_e32 v116, v245, v246
	v_fmamk_f32 v116, v116, 0x3a800000, v226
	v_rsq_f32_e32 v116, v116
	s_waitcnt vmcnt(5)
	v_lshlrev_b32_e32 v120, 16, v144
	v_and_b32_e32 v121, 0xffff0000, v144
	v_lshlrev_b32_e32 v122, 16, v145
	s_waitcnt lgkmcnt(0)
	v_pk_mul_f32 v[112:113], v[112:113], v[116:117] op_sel_hi:[1,0]
	v_pk_mul_f32 v[114:115], v[114:115], v[116:117] op_sel_hi:[1,0]
	v_pk_mul_f32 v[112:113], v[112:113], s[14:15] op_sel_hi:[1,0]
	v_pk_mul_f32 v[108:109], v[108:109], v[116:117] op_sel_hi:[1,0]
	v_pk_mul_f32 v[114:115], v[114:115], s[14:15] op_sel_hi:[1,0]
	v_exp_f32_e32 v112, v112
	v_exp_f32_e32 v113, v113
	v_pk_mul_f32 v[110:111], v[110:111], v[116:117] op_sel_hi:[1,0]
	v_pk_mul_f32 v[108:109], v[108:109], s[14:15] op_sel_hi:[1,0]
	v_exp_f32_e32 v114, v114
	v_exp_f32_e32 v115, v115
	v_pk_mul_f32 v[110:111], v[110:111], s[14:15] op_sel_hi:[1,0]
	v_exp_f32_e32 v108, v108
	v_exp_f32_e32 v109, v109
	v_exp_f32_e32 v110, v110
	v_exp_f32_e32 v111, v111
	v_pk_add_f32 v[112:113], v[112:113], 1.0 op_sel_hi:[1,0]
	v_pk_add_f32 v[114:115], v[114:115], 1.0 op_sel_hi:[1,0]
	v_rcp_f32_e32 v112, v112
	v_rcp_f32_e32 v113, v113
	v_pk_add_f32 v[108:109], v[108:109], 1.0 op_sel_hi:[1,0]
	v_rcp_f32_e32 v114, v114
	v_rcp_f32_e32 v115, v115
	v_pk_add_f32 v[110:111], v[110:111], 1.0 op_sel_hi:[1,0]
	v_rcp_f32_e32 v108, v108
	v_rcp_f32_e32 v109, v109
	v_rcp_f32_e32 v110, v110
	v_rcp_f32_e32 v111, v111
	v_and_b32_e32 v123, 0xffff0000, v145
	v_lshlrev_b32_e32 v144, 16, v140
	v_and_b32_e32 v145, 0xffff0000, v140
	v_lshlrev_b64 v[118:119], 11, v[190:191]
	v_lshlrev_b32_e32 v156, 16, v146
	v_and_b32_e32 v157, 0xffff0000, v146
	v_lshlrev_b32_e32 v140, 16, v141
	v_and_b32_e32 v141, 0xffff0000, v141
	v_pk_fma_f32 v[144:145], v[112:113], v[120:121], v[144:145]
	v_lshlrev_b32_e32 v112, 16, v142
	v_and_b32_e32 v113, 0xffff0000, v142
	v_lshlrev_b32_e32 v146, 16, v147
	v_and_b32_e32 v147, 0xffff0000, v147
	v_pk_fma_f32 v[140:141], v[114:115], v[122:123], v[140:141]
	v_lshlrev_b32_e32 v114, 16, v143
	v_and_b32_e32 v115, 0xffff0000, v143
	v_pk_fma_f32 v[142:143], v[108:109], v[156:157], v[112:113]
	v_lshl_add_u64 v[108:109], s[72:73], 0, v[118:119]
	v_pk_fma_f32 v[146:147], v[110:111], v[146:147], v[114:115]
	s_and_b64 vcc, exec, s[28:29]
	v_lshl_add_u64 v[108:109], v[198:199], 1, v[108:109]
	s_cbranch_vccz .LBB0_442
	v_cvt_pk_bf16_f32 v110, v144, v145
	v_cvt_pk_bf16_f32 v111, v140, v141
	v_cvt_pk_bf16_f32 v112, v142, v143
	v_cvt_pk_bf16_f32 v113, v146, v147
	global_store_dwordx4 v[108:109], v[110:113], off
.LBB0_442:
	v_mov_b32_e32 v117, v116
	s_nop 0
	v_mov_b32_e32 v110, v116
	v_mov_b32_e32 v111, v116
	v_pk_mul_f32 v[106:107], v[106:107], v[110:111]
	v_pk_mul_f32 v[104:105], v[104:105], v[116:117]
	v_pk_mul_f32 v[106:107], v[106:107], s[14:15] op_sel_hi:[1,0]
	v_pk_mul_f32 v[104:105], v[104:105], s[14:15] op_sel_hi:[1,0]
	v_pk_mul_f32 v[102:103], v[102:103], v[110:111]
	v_pk_mul_f32 v[100:101], v[100:101], v[116:117]
	v_exp_f32_e32 v104, v104
	v_exp_f32_e32 v106, v106
	v_exp_f32_e32 v107, v107
	v_exp_f32_e32 v105, v105
	v_pk_mul_f32 v[102:103], v[102:103], s[14:15] op_sel_hi:[1,0]
	v_pk_mul_f32 v[100:101], v[100:101], s[14:15] op_sel_hi:[1,0]
	v_exp_f32_e32 v102, v102
	v_exp_f32_e32 v100, v100
	v_exp_f32_e32 v103, v103
	v_exp_f32_e32 v101, v101
	v_pk_add_f32 v[106:107], v[106:107], 1.0 op_sel_hi:[1,0]
	v_pk_add_f32 v[104:105], v[104:105], 1.0 op_sel_hi:[1,0]
	v_rcp_f32_e32 v106, v106
	v_rcp_f32_e32 v104, v104
	v_rcp_f32_e32 v105, v105
	v_rcp_f32_e32 v107, v107
	v_pk_add_f32 v[102:103], v[102:103], 1.0 op_sel_hi:[1,0]
	v_pk_add_f32 v[100:101], v[100:101], 1.0 op_sel_hi:[1,0]
	v_rcp_f32_e32 v102, v102
	v_rcp_f32_e32 v100, v100
	v_rcp_f32_e32 v101, v101
	v_rcp_f32_e32 v103, v103
	s_waitcnt vmcnt(4)
	v_lshlrev_b32_e32 v112, 16, v136
	v_and_b32_e32 v113, 0xffff0000, v136
	v_lshlrev_b32_e32 v110, 16, v137
	v_and_b32_e32 v111, 0xffff0000, v137
	v_lshlrev_b32_e32 v118, 16, v132
	v_and_b32_e32 v119, 0xffff0000, v132
	v_lshlrev_b32_e32 v120, 16, v133
	v_and_b32_e32 v121, 0xffff0000, v133
	v_lshlrev_b32_e32 v114, 16, v138
	v_and_b32_e32 v115, 0xffff0000, v138
	v_lshlrev_b32_e32 v116, 16, v139
	v_and_b32_e32 v117, 0xffff0000, v139
	v_pk_fma_f32 v[132:133], v[106:107], v[110:111], v[120:121]
	v_pk_fma_f32 v[136:137], v[104:105], v[112:113], v[118:119]
	v_lshlrev_b32_e32 v104, 16, v134
	v_and_b32_e32 v105, 0xffff0000, v134
	v_lshlrev_b32_e32 v106, 16, v135
	v_and_b32_e32 v107, 0xffff0000, v135
	v_pk_fma_f32 v[134:135], v[100:101], v[114:115], v[104:105]
	v_pk_fma_f32 v[138:139], v[102:103], v[116:117], v[106:107]
	s_and_b64 vcc, exec, s[28:29]
	s_cbranch_vccz .LBB0_444
	v_cvt_pk_bf16_f32 v100, v136, v137
	v_cvt_pk_bf16_f32 v101, v132, v133
	v_cvt_pk_bf16_f32 v102, v134, v135
	v_cvt_pk_bf16_f32 v103, v138, v139
	global_store_dwordx4 v[108:109], v[100:103], off offset:256

.LBB0_446:
	s_or_b64 exec, exec, s[4:5]
	v_add_f32_e32 v100, v243, v244
	v_fmamk_f32 v100, v100, 0x3a800000, v226
	v_rsq_f32_e32 v156, v100
	s_waitcnt lgkmcnt(0)
	v_lshlrev_b64 v[100:101], 10, v[188:189]
	v_lshl_add_u64 v[100:101], v[100:101], 0, v[198:199]
	v_lshlrev_b64 v[100:101], 1, v[100:101]
	v_lshl_add_u64 v[102:103], s[42:43], 0, v[100:101]
	global_load_dwordx4 v[160:163], v[102:103], off
	v_or_b32_e32 v100, 0x100, v100
	v_lshl_add_u64 v[102:103], s[42:43], 0, v[100:101]
	global_load_dwordx4 v[116:119], v[102:103], off
	v_lshlrev_b64 v[100:101], 10, v[186:187]
	v_lshl_add_u64 v[100:101], v[100:101], 0, v[198:199]
	v_lshlrev_b64 v[104:105], 1, v[100:101]
	v_lshl_add_u64 v[100:101], s[42:43], 0, v[104:105]
	global_load_dwordx4 v[108:111], v[100:101], off
	v_or_b32_e32 v104, 0x100, v104
	v_lshl_add_u64 v[100:101], s[42:43], 0, v[104:105]
	global_load_dwordx4 v[100:103], v[100:101], off
	v_pk_mul_f32 v[96:97], v[96:97], v[156:157] op_sel_hi:[1,0]
	v_pk_mul_f32 v[98:99], v[98:99], v[156:157] op_sel_hi:[1,0]
	s_waitcnt vmcnt(4)
	v_mov_b32_e32 v216, v164
	v_mov_b32_e32 v217, v165
	v_mov_b32_e32 v218, v166
	v_mov_b32_e32 v219, v167
	v_mov_b32_e32 v120, v168
	v_mov_b32_e32 v121, v169
	v_mov_b32_e32 v122, v170
	v_mov_b32_e32 v123, v171
	v_mov_b32_e32 v112, v174
	v_mov_b32_e32 v113, v175
	v_mov_b32_e32 v114, v176
	v_mov_b32_e32 v115, v177
	v_mov_b32_e32 v104, v220
	v_mov_b32_e32 v105, v221
	v_mov_b32_e32 v106, v222
	v_mov_b32_e32 v107, v223
	v_lshl_add_u32 v228, v184, 10, v198
	v_lshlrev_b32_e32 v228, 1, v228
	global_load_dwordx4 v[164:167], v228, s[44:45]
	global_load_dwordx4 v[168:171], v228, s[44:45] offset:256
	v_lshl_add_u32 v228, v182, 10, v198
	v_lshlrev_b32_e32 v228, 1, v228
	global_load_dwordx4 v[174:177], v228, s[44:45]
	global_load_dwordx4 v[220:223], v228, s[44:45] offset:256
	v_pk_mul_f32 v[96:97], v[96:97], s[14:15] op_sel_hi:[1,0]
	v_pk_mul_f32 v[98:99], v[98:99], s[14:15] op_sel_hi:[1,0]
	v_pk_mul_f32 v[92:93], v[92:93], v[156:157] op_sel_hi:[1,0]
	v_pk_mul_f32 v[94:95], v[94:95], v[156:157] op_sel_hi:[1,0]
	v_exp_f32_e32 v96, v96
	v_exp_f32_e32 v97, v97
	v_exp_f32_e32 v98, v98
	v_exp_f32_e32 v99, v99
	v_pk_mul_f32 v[94:95], v[94:95], s[14:15] op_sel_hi:[1,0]
	v_pk_mul_f32 v[92:93], v[92:93], s[14:15] op_sel_hi:[1,0]
	v_exp_f32_e32 v94, v94
	v_exp_f32_e32 v92, v92
	v_exp_f32_e32 v93, v93
	v_exp_f32_e32 v95, v95
	v_pk_add_f32 v[98:99], v[98:99], 1.0 op_sel_hi:[1,0]
	v_pk_add_f32 v[96:97], v[96:97], 1.0 op_sel_hi:[1,0]
	v_pk_add_f32 v[92:93], v[92:93], 1.0 op_sel_hi:[1,0]
	v_rcp_f32_e32 v194, v96
	v_rcp_f32_e32 v195, v97
	v_rcp_f32_e32 v96, v98
	v_rcp_f32_e32 v97, v99
	v_pk_add_f32 v[94:95], v[94:95], 1.0 op_sel_hi:[1,0]
	v_rcp_f32_e32 v92, v92
	v_rcp_f32_e32 v93, v93
	v_lshlrev_b64 v[158:159], 11, v[188:189]
	v_lshl_add_u64 v[158:159], s[72:73], 0, v[158:159]
	s_and_b64 vcc, exec, s[28:29]
	v_lshl_add_u64 v[158:159], v[198:199], 1, v[158:159]
	s_waitcnt vmcnt(7)
	v_lshlrev_b32_e32 v230, 16, v160
	v_and_b32_e32 v231, 0xffff0000, v160
	v_lshlrev_b32_e32 v160, 16, v161
	s_waitcnt vmcnt(7)
	v_lshlrev_b32_e32 v98, 16, v216
	v_and_b32_e32 v99, 0xffff0000, v216
	v_lshlrev_b32_e32 v196, 16, v217
	v_and_b32_e32 v197, 0xffff0000, v217
	v_rcp_f32_e32 v216, v94
	v_rcp_f32_e32 v217, v95
	v_and_b32_e32 v161, 0xffff0000, v161
	v_lshlrev_b32_e32 v94, 16, v218
	v_and_b32_e32 v95, 0xffff0000, v218
	v_lshlrev_b32_e32 v218, 16, v219
	v_and_b32_e32 v219, 0xffff0000, v219
	v_pk_fma_f32 v[96:97], v[96:97], v[196:197], v[160:161]
	v_lshlrev_b32_e32 v160, 16, v162
	v_and_b32_e32 v161, 0xffff0000, v162
	v_lshlrev_b32_e32 v162, 16, v163
	v_and_b32_e32 v163, 0xffff0000, v163
	v_pk_fma_f32 v[98:99], v[194:195], v[98:99], v[230:231]
	v_pk_fma_f32 v[94:95], v[92:93], v[94:95], v[160:161]
	v_pk_fma_f32 v[92:93], v[216:217], v[218:219], v[162:163]
	s_cbranch_vccz .LBB0_448
	v_cvt_pk_bf16_f32 v160, v98, v99
	v_cvt_pk_bf16_f32 v161, v96, v97
	v_cvt_pk_bf16_f32 v162, v94, v95
	v_cvt_pk_bf16_f32 v163, v92, v93
	global_store_dwordx4 v[158:159], v[160:163], off
.LBB0_448:
	v_mov_b32_e32 v157, v156
	s_nop 0
	v_mov_b32_e32 v160, v156
	v_mov_b32_e32 v161, v156
	v_pk_mul_f32 v[90:91], v[90:91], v[160:161]
	v_pk_mul_f32 v[88:89], v[88:89], v[156:157]
	v_pk_mul_f32 v[90:91], v[90:91], s[14:15] op_sel_hi:[1,0]
	v_pk_mul_f32 v[88:89], v[88:89], s[14:15] op_sel_hi:[1,0]
	v_pk_mul_f32 v[86:87], v[86:87], v[160:161]
	v_pk_mul_f32 v[84:85], v[84:85], v[156:157]
	v_exp_f32_e32 v88, v88
	v_exp_f32_e32 v90, v90
	v_exp_f32_e32 v91, v91
	v_exp_f32_e32 v89, v89
	v_pk_mul_f32 v[86:87], v[86:87], s[14:15] op_sel_hi:[1,0]
	v_pk_mul_f32 v[84:85], v[84:85], s[14:15] op_sel_hi:[1,0]
	v_exp_f32_e32 v86, v86
	v_exp_f32_e32 v84, v84
	v_exp_f32_e32 v87, v87
	v_exp_f32_e32 v85, v85
	v_pk_add_f32 v[90:91], v[90:91], 1.0 op_sel_hi:[1,0]
	v_pk_add_f32 v[88:89], v[88:89], 1.0 op_sel_hi:[1,0]
	v_rcp_f32_e32 v90, v90
	v_rcp_f32_e32 v88, v88
	v_rcp_f32_e32 v89, v89
	v_rcp_f32_e32 v91, v91
	v_pk_add_f32 v[86:87], v[86:87], 1.0 op_sel_hi:[1,0]
	v_pk_add_f32 v[84:85], v[84:85], 1.0 op_sel_hi:[1,0]
	v_rcp_f32_e32 v86, v86
	v_rcp_f32_e32 v84, v84
	v_rcp_f32_e32 v85, v85
	v_rcp_f32_e32 v87, v87
	s_waitcnt vmcnt(6)
	v_lshlrev_b32_e32 v162, 16, v120
	v_and_b32_e32 v163, 0xffff0000, v120
	v_lshlrev_b32_e32 v120, 16, v121
	v_and_b32_e32 v121, 0xffff0000, v121
	v_lshlrev_b32_e32 v160, 16, v116
	v_and_b32_e32 v161, 0xffff0000, v116
	v_lshlrev_b32_e32 v116, 16, v117
	v_and_b32_e32 v117, 0xffff0000, v117
	v_lshlrev_b32_e32 v156, 16, v122
	v_and_b32_e32 v157, 0xffff0000, v122
	v_lshlrev_b32_e32 v122, 16, v123
	v_and_b32_e32 v123, 0xffff0000, v123
	v_pk_fma_f32 v[116:117], v[90:91], v[120:121], v[116:117]
	v_pk_fma_f32 v[120:121], v[88:89], v[162:163], v[160:161]
	v_lshlrev_b32_e32 v88, 16, v118
	v_and_b32_e32 v89, 0xffff0000, v118
	v_lshlrev_b32_e32 v90, 16, v119
	v_and_b32_e32 v91, 0xffff0000, v119
	v_pk_fma_f32 v[118:119], v[84:85], v[156:157], v[88:89]
	v_pk_fma_f32 v[122:123], v[86:87], v[122:123], v[90:91]
	s_and_b64 vcc, exec, s[28:29]
	s_cbranch_vccz .LBB0_450
	v_cvt_pk_bf16_f32 v84, v120, v121
	v_cvt_pk_bf16_f32 v85, v116, v117
	v_cvt_pk_bf16_f32 v86, v118, v119
	v_cvt_pk_bf16_f32 v87, v122, v123
	global_store_dwordx4 v[158:159], v[84:87], off offset:256

.LBB0_452:
	s_or_b64 exec, exec, s[4:5]
	v_add_f32_e32 v84, v241, v242
	v_fmamk_f32 v84, v84, 0x3a800000, v226
	v_rsq_f32_e32 v84, v84
	s_waitcnt vmcnt(5)
	v_lshlrev_b32_e32 v88, 16, v112
	v_and_b32_e32 v89, 0xffff0000, v112
	v_lshlrev_b32_e32 v90, 16, v113
	s_waitcnt lgkmcnt(0)
	v_pk_mul_f32 v[80:81], v[80:81], v[84:85] op_sel_hi:[1,0]
	v_pk_mul_f32 v[82:83], v[82:83], v[84:85] op_sel_hi:[1,0]
	v_pk_mul_f32 v[80:81], v[80:81], s[14:15] op_sel_hi:[1,0]
	v_pk_mul_f32 v[76:77], v[76:77], v[84:85] op_sel_hi:[1,0]
	v_pk_mul_f32 v[82:83], v[82:83], s[14:15] op_sel_hi:[1,0]
	v_exp_f32_e32 v80, v80
	v_exp_f32_e32 v81, v81
	v_pk_mul_f32 v[78:79], v[78:79], v[84:85] op_sel_hi:[1,0]
	v_pk_mul_f32 v[76:77], v[76:77], s[14:15] op_sel_hi:[1,0]
	v_exp_f32_e32 v82, v82
	v_exp_f32_e32 v83, v83
	v_pk_mul_f32 v[78:79], v[78:79], s[14:15] op_sel_hi:[1,0]
	v_exp_f32_e32 v76, v76
	v_exp_f32_e32 v77, v77
	v_exp_f32_e32 v78, v78
	v_exp_f32_e32 v79, v79
	v_pk_add_f32 v[80:81], v[80:81], 1.0 op_sel_hi:[1,0]
	v_pk_add_f32 v[82:83], v[82:83], 1.0 op_sel_hi:[1,0]
	v_rcp_f32_e32 v80, v80
	v_rcp_f32_e32 v81, v81
	v_pk_add_f32 v[76:77], v[76:77], 1.0 op_sel_hi:[1,0]
	v_rcp_f32_e32 v82, v82
	v_rcp_f32_e32 v83, v83
	v_pk_add_f32 v[78:79], v[78:79], 1.0 op_sel_hi:[1,0]
	v_rcp_f32_e32 v76, v76
	v_rcp_f32_e32 v77, v77
	v_rcp_f32_e32 v78, v78
	v_rcp_f32_e32 v79, v79
	v_and_b32_e32 v91, 0xffff0000, v113
	v_lshlrev_b32_e32 v112, 16, v108
	v_and_b32_e32 v113, 0xffff0000, v108
	v_lshlrev_b64 v[86:87], 11, v[186:187]
	v_lshlrev_b32_e32 v156, 16, v114
	v_and_b32_e32 v157, 0xffff0000, v114
	v_lshlrev_b32_e32 v108, 16, v109
	v_and_b32_e32 v109, 0xffff0000, v109
	v_pk_fma_f32 v[112:113], v[80:81], v[88:89], v[112:113]
	v_lshlrev_b32_e32 v80, 16, v110
	v_and_b32_e32 v81, 0xffff0000, v110
	v_lshlrev_b32_e32 v114, 16, v115
	v_and_b32_e32 v115, 0xffff0000, v115
	v_pk_fma_f32 v[108:109], v[82:83], v[90:91], v[108:109]
	v_lshlrev_b32_e32 v82, 16, v111
	v_and_b32_e32 v83, 0xffff0000, v111
	v_pk_fma_f32 v[110:111], v[76:77], v[156:157], v[80:81]
	v_lshl_add_u64 v[76:77], s[72:73], 0, v[86:87]
	v_pk_fma_f32 v[114:115], v[78:79], v[114:115], v[82:83]
	s_and_b64 vcc, exec, s[28:29]
	v_lshl_add_u64 v[76:77], v[198:199], 1, v[76:77]
	s_cbranch_vccz .LBB0_454
	v_cvt_pk_bf16_f32 v78, v112, v113
	v_cvt_pk_bf16_f32 v79, v108, v109
	v_cvt_pk_bf16_f32 v80, v110, v111
	v_cvt_pk_bf16_f32 v81, v114, v115
	global_store_dwordx4 v[76:77], v[78:81], off
.LBB0_454:
	v_mov_b32_e32 v85, v84
	s_nop 0
	v_mov_b32_e32 v78, v84
	v_mov_b32_e32 v79, v84
	v_pk_mul_f32 v[74:75], v[74:75], v[78:79]
	v_pk_mul_f32 v[72:73], v[72:73], v[84:85]
	v_pk_mul_f32 v[74:75], v[74:75], s[14:15] op_sel_hi:[1,0]
	v_pk_mul_f32 v[72:73], v[72:73], s[14:15] op_sel_hi:[1,0]
	v_pk_mul_f32 v[70:71], v[70:71], v[78:79]
	v_pk_mul_f32 v[68:69], v[68:69], v[84:85]
	v_exp_f32_e32 v72, v72
	v_exp_f32_e32 v74, v74
	v_exp_f32_e32 v75, v75
	v_exp_f32_e32 v73, v73
	v_pk_mul_f32 v[70:71], v[70:71], s[14:15] op_sel_hi:[1,0]
	v_pk_mul_f32 v[68:69], v[68:69], s[14:15] op_sel_hi:[1,0]
	v_exp_f32_e32 v70, v70
	v_exp_f32_e32 v68, v68
	v_exp_f32_e32 v71, v71
	v_exp_f32_e32 v69, v69
	v_pk_add_f32 v[74:75], v[74:75], 1.0 op_sel_hi:[1,0]
	v_pk_add_f32 v[72:73], v[72:73], 1.0 op_sel_hi:[1,0]
	v_rcp_f32_e32 v74, v74
	v_rcp_f32_e32 v72, v72
	v_rcp_f32_e32 v73, v73
	v_rcp_f32_e32 v75, v75
	v_pk_add_f32 v[70:71], v[70:71], 1.0 op_sel_hi:[1,0]
	v_pk_add_f32 v[68:69], v[68:69], 1.0 op_sel_hi:[1,0]
	v_rcp_f32_e32 v70, v70
	v_rcp_f32_e32 v68, v68
	v_rcp_f32_e32 v69, v69
	v_rcp_f32_e32 v71, v71
	s_waitcnt vmcnt(4)
	v_lshlrev_b32_e32 v80, 16, v104
	v_and_b32_e32 v81, 0xffff0000, v104
	v_lshlrev_b32_e32 v78, 16, v105
	v_and_b32_e32 v79, 0xffff0000, v105
	v_lshlrev_b32_e32 v86, 16, v100
	v_and_b32_e32 v87, 0xffff0000, v100
	v_lshlrev_b32_e32 v88, 16, v101
	v_and_b32_e32 v89, 0xffff0000, v101
	v_lshlrev_b32_e32 v82, 16, v106
	v_and_b32_e32 v83, 0xffff0000, v106
	v_lshlrev_b32_e32 v84, 16, v107
	v_and_b32_e32 v85, 0xffff0000, v107
	v_pk_fma_f32 v[100:101], v[74:75], v[78:79], v[88:89]
	v_pk_fma_f32 v[104:105], v[72:73], v[80:81], v[86:87]
	v_lshlrev_b32_e32 v72, 16, v102
	v_and_b32_e32 v73, 0xffff0000, v102
	v_lshlrev_b32_e32 v74, 16, v103
	v_and_b32_e32 v75, 0xffff0000, v103
	v_pk_fma_f32 v[102:103], v[68:69], v[82:83], v[72:73]
	v_pk_fma_f32 v[106:107], v[70:71], v[84:85], v[74:75]
	s_and_b64 vcc, exec, s[28:29]
	s_cbranch_vccz .LBB0_456
	v_cvt_pk_bf16_f32 v68, v104, v105
	v_cvt_pk_bf16_f32 v69, v100, v101
	v_cvt_pk_bf16_f32 v70, v102, v103
	v_cvt_pk_bf16_f32 v71, v106, v107
	global_store_dwordx4 v[76:77], v[68:71], off offset:256

.LBB0_458:
	s_or_b64 exec, exec, s[4:5]
	v_add_f32_e32 v68, v239, v240
	v_fmamk_f32 v68, v68, 0x3a800000, v226
	v_rsq_f32_e32 v156, v68
	s_waitcnt lgkmcnt(0)
	v_lshlrev_b64 v[68:69], 10, v[184:185]
	v_lshl_add_u64 v[68:69], v[68:69], 0, v[198:199]
	v_lshlrev_b64 v[68:69], 1, v[68:69]
	v_lshl_add_u64 v[70:71], s[42:43], 0, v[68:69]
	global_load_dwordx4 v[160:163], v[70:71], off
	v_or_b32_e32 v68, 0x100, v68
	v_lshl_add_u64 v[70:71], s[42:43], 0, v[68:69]
	global_load_dwordx4 v[84:87], v[70:71], off
	v_lshlrev_b64 v[68:69], 10, v[182:183]
	v_lshl_add_u64 v[68:69], v[68:69], 0, v[198:199]
	v_lshlrev_b64 v[72:73], 1, v[68:69]
	v_lshl_add_u64 v[68:69], s[42:43], 0, v[72:73]
	global_load_dwordx4 v[76:79], v[68:69], off
	v_or_b32_e32 v72, 0x100, v72
	v_lshl_add_u64 v[68:69], s[42:43], 0, v[72:73]
	global_load_dwordx4 v[68:71], v[68:69], off
	v_pk_mul_f32 v[64:65], v[64:65], v[156:157] op_sel_hi:[1,0]
	v_pk_mul_f32 v[66:67], v[66:67], v[156:157] op_sel_hi:[1,0]
	s_waitcnt vmcnt(4)
	v_mov_b32_e32 v216, v164
	v_mov_b32_e32 v217, v165
	v_mov_b32_e32 v218, v166
	v_mov_b32_e32 v219, v167
	v_mov_b32_e32 v88, v168
	v_mov_b32_e32 v89, v169
	v_mov_b32_e32 v90, v170
	v_mov_b32_e32 v91, v171
	v_mov_b32_e32 v80, v174
	v_mov_b32_e32 v81, v175
	v_mov_b32_e32 v82, v176
	v_mov_b32_e32 v83, v177
	v_mov_b32_e32 v72, v220
	v_mov_b32_e32 v73, v221
	v_mov_b32_e32 v74, v222
	v_mov_b32_e32 v75, v223
	v_lshl_add_u32 v228, v180, 10, v198
	v_lshlrev_b32_e32 v228, 1, v228
	global_load_dwordx4 v[164:167], v228, s[44:45]
	global_load_dwordx4 v[168:171], v228, s[44:45] offset:256
	v_lshl_add_u32 v228, v178, 10, v198
	v_lshlrev_b32_e32 v228, 1, v228
	global_load_dwordx4 v[174:177], v228, s[44:45]
	global_load_dwordx4 v[220:223], v228, s[44:45] offset:256
	v_pk_mul_f32 v[64:65], v[64:65], s[14:15] op_sel_hi:[1,0]
	v_pk_mul_f32 v[66:67], v[66:67], s[14:15] op_sel_hi:[1,0]
	v_pk_mul_f32 v[60:61], v[60:61], v[156:157] op_sel_hi:[1,0]
	v_pk_mul_f32 v[62:63], v[62:63], v[156:157] op_sel_hi:[1,0]
	v_exp_f32_e32 v64, v64
	v_exp_f32_e32 v65, v65
	v_exp_f32_e32 v66, v66
	v_exp_f32_e32 v67, v67
	v_pk_mul_f32 v[62:63], v[62:63], s[14:15] op_sel_hi:[1,0]
	v_pk_mul_f32 v[60:61], v[60:61], s[14:15] op_sel_hi:[1,0]
	v_exp_f32_e32 v62, v62
	v_exp_f32_e32 v60, v60
	v_exp_f32_e32 v61, v61
	v_exp_f32_e32 v63, v63
	v_pk_add_f32 v[66:67], v[66:67], 1.0 op_sel_hi:[1,0]
	v_pk_add_f32 v[64:65], v[64:65], 1.0 op_sel_hi:[1,0]
	v_pk_add_f32 v[60:61], v[60:61], 1.0 op_sel_hi:[1,0]
	v_rcp_f32_e32 v194, v64
	v_rcp_f32_e32 v195, v65
	v_rcp_f32_e32 v64, v66
	v_rcp_f32_e32 v65, v67
	v_pk_add_f32 v[62:63], v[62:63], 1.0 op_sel_hi:[1,0]
	v_rcp_f32_e32 v60, v60
	v_rcp_f32_e32 v61, v61
	v_lshlrev_b64 v[158:159], 11, v[184:185]
	v_lshl_add_u64 v[158:159], s[72:73], 0, v[158:159]
	s_and_b64 vcc, exec, s[28:29]
	v_lshl_add_u64 v[158:159], v[198:199], 1, v[158:159]
	s_waitcnt vmcnt(7)
	v_lshlrev_b32_e32 v230, 16, v160
	v_and_b32_e32 v231, 0xffff0000, v160
	v_lshlrev_b32_e32 v160, 16, v161
	s_waitcnt vmcnt(7)
	v_lshlrev_b32_e32 v66, 16, v216
	v_and_b32_e32 v67, 0xffff0000, v216
	v_lshlrev_b32_e32 v196, 16, v217
	v_and_b32_e32 v197, 0xffff0000, v217
	v_rcp_f32_e32 v216, v62
	v_rcp_f32_e32 v217, v63
	v_and_b32_e32 v161, 0xffff0000, v161
	v_lshlrev_b32_e32 v62, 16, v218
	v_and_b32_e32 v63, 0xffff0000, v218
	v_lshlrev_b32_e32 v218, 16, v219
	v_and_b32_e32 v219, 0xffff0000, v219
	v_pk_fma_f32 v[64:65], v[64:65], v[196:197], v[160:161]
	v_lshlrev_b32_e32 v160, 16, v162
	v_and_b32_e32 v161, 0xffff0000, v162
	v_lshlrev_b32_e32 v162, 16, v163
	v_and_b32_e32 v163, 0xffff0000, v163
	v_pk_fma_f32 v[66:67], v[194:195], v[66:67], v[230:231]
	v_pk_fma_f32 v[62:63], v[60:61], v[62:63], v[160:161]
	v_pk_fma_f32 v[60:61], v[216:217], v[218:219], v[162:163]
	s_cbranch_vccz .LBB0_460
	v_cvt_pk_bf16_f32 v160, v66, v67
	v_cvt_pk_bf16_f32 v161, v64, v65
	v_cvt_pk_bf16_f32 v162, v62, v63
	v_cvt_pk_bf16_f32 v163, v60, v61
	global_store_dwordx4 v[158:159], v[160:163], off
.LBB0_460:
	v_mov_b32_e32 v157, v156
	s_nop 0
	v_mov_b32_e32 v160, v156
	v_mov_b32_e32 v161, v156
	v_pk_mul_f32 v[58:59], v[58:59], v[160:161]
	v_pk_mul_f32 v[56:57], v[56:57], v[156:157]
	v_pk_mul_f32 v[58:59], v[58:59], s[14:15] op_sel_hi:[1,0]
	v_pk_mul_f32 v[56:57], v[56:57], s[14:15] op_sel_hi:[1,0]
	v_pk_mul_f32 v[54:55], v[54:55], v[160:161]
	v_pk_mul_f32 v[52:53], v[52:53], v[156:157]
	v_exp_f32_e32 v56, v56
	v_exp_f32_e32 v58, v58
	v_exp_f32_e32 v59, v59
	v_exp_f32_e32 v57, v57
	v_pk_mul_f32 v[54:55], v[54:55], s[14:15] op_sel_hi:[1,0]
	v_pk_mul_f32 v[52:53], v[52:53], s[14:15] op_sel_hi:[1,0]
	v_exp_f32_e32 v54, v54
	v_exp_f32_e32 v52, v52
	v_exp_f32_e32 v55, v55
	v_exp_f32_e32 v53, v53
	v_pk_add_f32 v[58:59], v[58:59], 1.0 op_sel_hi:[1,0]
	v_pk_add_f32 v[56:57], v[56:57], 1.0 op_sel_hi:[1,0]
	v_rcp_f32_e32 v58, v58
	v_rcp_f32_e32 v56, v56
	v_rcp_f32_e32 v57, v57
	v_rcp_f32_e32 v59, v59
	v_pk_add_f32 v[54:55], v[54:55], 1.0 op_sel_hi:[1,0]
	v_pk_add_f32 v[52:53], v[52:53], 1.0 op_sel_hi:[1,0]
	v_rcp_f32_e32 v54, v54
	v_rcp_f32_e32 v52, v52
	v_rcp_f32_e32 v53, v53
	v_rcp_f32_e32 v55, v55
	s_waitcnt vmcnt(6)
	v_lshlrev_b32_e32 v162, 16, v88
	v_and_b32_e32 v163, 0xffff0000, v88
	v_lshlrev_b32_e32 v88, 16, v89
	v_and_b32_e32 v89, 0xffff0000, v89
	v_lshlrev_b32_e32 v160, 16, v84
	v_and_b32_e32 v161, 0xffff0000, v84
	v_lshlrev_b32_e32 v84, 16, v85
	v_and_b32_e32 v85, 0xffff0000, v85
	v_lshlrev_b32_e32 v156, 16, v90
	v_and_b32_e32 v157, 0xffff0000, v90
	v_lshlrev_b32_e32 v90, 16, v91
	v_and_b32_e32 v91, 0xffff0000, v91
	v_pk_fma_f32 v[84:85], v[58:59], v[88:89], v[84:85]
	v_pk_fma_f32 v[88:89], v[56:57], v[162:163], v[160:161]
	v_lshlrev_b32_e32 v56, 16, v86
	v_and_b32_e32 v57, 0xffff0000, v86
	v_lshlrev_b32_e32 v58, 16, v87
	v_and_b32_e32 v59, 0xffff0000, v87
	v_pk_fma_f32 v[86:87], v[52:53], v[156:157], v[56:57]
	v_pk_fma_f32 v[90:91], v[54:55], v[90:91], v[58:59]
	s_and_b64 vcc, exec, s[28:29]
	s_cbranch_vccz .LBB0_462
	v_cvt_pk_bf16_f32 v52, v88, v89
	v_cvt_pk_bf16_f32 v53, v84, v85
	v_cvt_pk_bf16_f32 v54, v86, v87
	v_cvt_pk_bf16_f32 v55, v90, v91
	global_store_dwordx4 v[158:159], v[52:55], off offset:256

.LBB0_464:
	s_or_b64 exec, exec, s[4:5]
	v_add_f32_e32 v52, v237, v238
	v_fmamk_f32 v52, v52, 0x3a800000, v226
	v_rsq_f32_e32 v52, v52
	s_waitcnt vmcnt(5)
	v_lshlrev_b32_e32 v56, 16, v80
	v_and_b32_e32 v57, 0xffff0000, v80
	v_lshlrev_b32_e32 v58, 16, v81
	s_waitcnt lgkmcnt(0)
	v_pk_mul_f32 v[48:49], v[48:49], v[52:53] op_sel_hi:[1,0]
	v_pk_mul_f32 v[50:51], v[50:51], v[52:53] op_sel_hi:[1,0]
	v_pk_mul_f32 v[48:49], v[48:49], s[14:15] op_sel_hi:[1,0]
	v_pk_mul_f32 v[44:45], v[44:45], v[52:53] op_sel_hi:[1,0]
	v_pk_mul_f32 v[50:51], v[50:51], s[14:15] op_sel_hi:[1,0]
	v_exp_f32_e32 v48, v48
	v_exp_f32_e32 v49, v49
	v_pk_mul_f32 v[46:47], v[46:47], v[52:53] op_sel_hi:[1,0]
	v_pk_mul_f32 v[44:45], v[44:45], s[14:15] op_sel_hi:[1,0]
	v_exp_f32_e32 v50, v50
	v_exp_f32_e32 v51, v51
	v_pk_mul_f32 v[46:47], v[46:47], s[14:15] op_sel_hi:[1,0]
	v_exp_f32_e32 v44, v44
	v_exp_f32_e32 v45, v45
	v_exp_f32_e32 v46, v46
	v_exp_f32_e32 v47, v47
	v_pk_add_f32 v[48:49], v[48:49], 1.0 op_sel_hi:[1,0]
	v_pk_add_f32 v[50:51], v[50:51], 1.0 op_sel_hi:[1,0]
	v_rcp_f32_e32 v48, v48
	v_rcp_f32_e32 v49, v49
	v_pk_add_f32 v[44:45], v[44:45], 1.0 op_sel_hi:[1,0]
	v_rcp_f32_e32 v50, v50
	v_rcp_f32_e32 v51, v51
	v_pk_add_f32 v[46:47], v[46:47], 1.0 op_sel_hi:[1,0]
	v_rcp_f32_e32 v44, v44
	v_rcp_f32_e32 v45, v45
	v_rcp_f32_e32 v46, v46
	v_rcp_f32_e32 v47, v47
	v_and_b32_e32 v59, 0xffff0000, v81
	v_lshlrev_b32_e32 v80, 16, v76
	v_and_b32_e32 v81, 0xffff0000, v76
	v_lshlrev_b64 v[54:55], 11, v[182:183]
	v_lshlrev_b32_e32 v156, 16, v82
	v_and_b32_e32 v157, 0xffff0000, v82
	v_lshlrev_b32_e32 v76, 16, v77
	v_and_b32_e32 v77, 0xffff0000, v77
	v_pk_fma_f32 v[80:81], v[48:49], v[56:57], v[80:81]
	v_lshlrev_b32_e32 v48, 16, v78
	v_and_b32_e32 v49, 0xffff0000, v78
	v_lshlrev_b32_e32 v82, 16, v83
	v_and_b32_e32 v83, 0xffff0000, v83
	v_pk_fma_f32 v[76:77], v[50:51], v[58:59], v[76:77]
	v_lshlrev_b32_e32 v50, 16, v79
	v_and_b32_e32 v51, 0xffff0000, v79
	v_pk_fma_f32 v[78:79], v[44:45], v[156:157], v[48:49]
	v_lshl_add_u64 v[44:45], s[72:73], 0, v[54:55]
	v_pk_fma_f32 v[82:83], v[46:47], v[82:83], v[50:51]
	s_and_b64 vcc, exec, s[28:29]
	v_lshl_add_u64 v[44:45], v[198:199], 1, v[44:45]
	s_cbranch_vccz .LBB0_466
	v_cvt_pk_bf16_f32 v46, v80, v81
	v_cvt_pk_bf16_f32 v47, v76, v77
	v_cvt_pk_bf16_f32 v48, v78, v79
	v_cvt_pk_bf16_f32 v49, v82, v83
	global_store_dwordx4 v[44:45], v[46:49], off
.LBB0_466:
	v_mov_b32_e32 v53, v52
	s_nop 0
	v_mov_b32_e32 v46, v52
	v_mov_b32_e32 v47, v52
	v_pk_mul_f32 v[42:43], v[42:43], v[46:47]
	v_pk_mul_f32 v[40:41], v[40:41], v[52:53]
	v_pk_mul_f32 v[42:43], v[42:43], s[14:15] op_sel_hi:[1,0]
	v_pk_mul_f32 v[40:41], v[40:41], s[14:15] op_sel_hi:[1,0]
	v_pk_mul_f32 v[38:39], v[38:39], v[46:47]
	v_pk_mul_f32 v[36:37], v[36:37], v[52:53]
	v_exp_f32_e32 v40, v40
	v_exp_f32_e32 v42, v42
	v_exp_f32_e32 v43, v43
	v_exp_f32_e32 v41, v41
	v_pk_mul_f32 v[38:39], v[38:39], s[14:15] op_sel_hi:[1,0]
	v_pk_mul_f32 v[36:37], v[36:37], s[14:15] op_sel_hi:[1,0]
	v_exp_f32_e32 v38, v38
	v_exp_f32_e32 v36, v36
	v_exp_f32_e32 v39, v39
	v_exp_f32_e32 v37, v37
	v_pk_add_f32 v[42:43], v[42:43], 1.0 op_sel_hi:[1,0]
	v_pk_add_f32 v[40:41], v[40:41], 1.0 op_sel_hi:[1,0]
	v_rcp_f32_e32 v42, v42
	v_rcp_f32_e32 v40, v40
	v_rcp_f32_e32 v41, v41
	v_rcp_f32_e32 v43, v43
	v_pk_add_f32 v[38:39], v[38:39], 1.0 op_sel_hi:[1,0]
	v_pk_add_f32 v[36:37], v[36:37], 1.0 op_sel_hi:[1,0]
	v_rcp_f32_e32 v38, v38
	v_rcp_f32_e32 v36, v36
	v_rcp_f32_e32 v37, v37
	v_rcp_f32_e32 v39, v39
	s_waitcnt vmcnt(4)
	v_lshlrev_b32_e32 v48, 16, v72
	v_and_b32_e32 v49, 0xffff0000, v72
	v_lshlrev_b32_e32 v46, 16, v73
	v_and_b32_e32 v47, 0xffff0000, v73
	v_lshlrev_b32_e32 v54, 16, v68
	v_and_b32_e32 v55, 0xffff0000, v68
	v_lshlrev_b32_e32 v56, 16, v69
	v_and_b32_e32 v57, 0xffff0000, v69
	v_lshlrev_b32_e32 v50, 16, v74
	v_and_b32_e32 v51, 0xffff0000, v74
	v_lshlrev_b32_e32 v52, 16, v75
	v_and_b32_e32 v53, 0xffff0000, v75
	v_pk_fma_f32 v[68:69], v[42:43], v[46:47], v[56:57]
	v_pk_fma_f32 v[72:73], v[40:41], v[48:49], v[54:55]
	v_lshlrev_b32_e32 v40, 16, v70
	v_and_b32_e32 v41, 0xffff0000, v70
	v_lshlrev_b32_e32 v42, 16, v71
	v_and_b32_e32 v43, 0xffff0000, v71
	v_pk_fma_f32 v[70:71], v[36:37], v[50:51], v[40:41]
	v_pk_fma_f32 v[74:75], v[38:39], v[52:53], v[42:43]
	s_and_b64 vcc, exec, s[28:29]
	s_cbranch_vccz .LBB0_468
	v_cvt_pk_bf16_f32 v36, v72, v73
	v_cvt_pk_bf16_f32 v37, v68, v69
	v_cvt_pk_bf16_f32 v38, v70, v71
	v_cvt_pk_bf16_f32 v39, v74, v75
	global_store_dwordx4 v[44:45], v[36:39], off offset:256

.LBB0_470:
	s_or_b64 exec, exec, s[4:5]
	v_add_f32_e32 v36, v235, v236
	v_fmamk_f32 v36, v36, 0x3a800000, v226
	v_rsq_f32_e32 v156, v36
	s_waitcnt lgkmcnt(0)
	v_lshlrev_b64 v[36:37], 10, v[180:181]
	v_lshl_add_u64 v[36:37], v[36:37], 0, v[198:199]
	v_lshlrev_b64 v[36:37], 1, v[36:37]
	v_lshl_add_u64 v[38:39], s[42:43], 0, v[36:37]
	global_load_dwordx4 v[160:163], v[38:39], off
	v_or_b32_e32 v36, 0x100, v36
	v_lshl_add_u64 v[38:39], s[42:43], 0, v[36:37]
	global_load_dwordx4 v[52:55], v[38:39], off
	v_lshlrev_b64 v[36:37], 10, v[178:179]
	v_lshl_add_u64 v[36:37], v[36:37], 0, v[198:199]
	v_lshlrev_b64 v[40:41], 1, v[36:37]
	v_lshl_add_u64 v[36:37], s[42:43], 0, v[40:41]
	global_load_dwordx4 v[44:47], v[36:37], off
	v_or_b32_e32 v40, 0x100, v40
	v_lshl_add_u64 v[36:37], s[42:43], 0, v[40:41]
	global_load_dwordx4 v[36:39], v[36:37], off
	v_pk_mul_f32 v[32:33], v[32:33], v[156:157] op_sel_hi:[1,0]
	v_pk_mul_f32 v[34:35], v[34:35], v[156:157] op_sel_hi:[1,0]
	s_waitcnt vmcnt(4)
	v_mov_b32_e32 v216, v164
	v_mov_b32_e32 v217, v165
	v_mov_b32_e32 v218, v166
	v_mov_b32_e32 v219, v167
	v_mov_b32_e32 v56, v168
	v_mov_b32_e32 v57, v169
	v_mov_b32_e32 v58, v170
	v_mov_b32_e32 v59, v171
	v_mov_b32_e32 v48, v174
	v_mov_b32_e32 v49, v175
	v_mov_b32_e32 v50, v176
	v_mov_b32_e32 v51, v177
	v_mov_b32_e32 v40, v220
	v_mov_b32_e32 v41, v221
	v_mov_b32_e32 v42, v222
	v_mov_b32_e32 v43, v223
	v_pk_mul_f32 v[32:33], v[32:33], s[14:15] op_sel_hi:[1,0]
	v_pk_mul_f32 v[34:35], v[34:35], s[14:15] op_sel_hi:[1,0]
	v_pk_mul_f32 v[28:29], v[28:29], v[156:157] op_sel_hi:[1,0]
	v_pk_mul_f32 v[30:31], v[30:31], v[156:157] op_sel_hi:[1,0]
	v_exp_f32_e32 v32, v32
	v_exp_f32_e32 v33, v33
	v_exp_f32_e32 v34, v34
	v_exp_f32_e32 v35, v35
	v_pk_mul_f32 v[30:31], v[30:31], s[14:15] op_sel_hi:[1,0]
	v_pk_mul_f32 v[28:29], v[28:29], s[14:15] op_sel_hi:[1,0]
	v_exp_f32_e32 v30, v30
	v_exp_f32_e32 v28, v28
	v_exp_f32_e32 v29, v29
	v_exp_f32_e32 v31, v31
	v_pk_add_f32 v[34:35], v[34:35], 1.0 op_sel_hi:[1,0]
	v_pk_add_f32 v[32:33], v[32:33], 1.0 op_sel_hi:[1,0]
	v_pk_add_f32 v[28:29], v[28:29], 1.0 op_sel_hi:[1,0]
	v_rcp_f32_e32 v194, v32
	v_rcp_f32_e32 v195, v33
	v_rcp_f32_e32 v32, v34
	v_rcp_f32_e32 v33, v35
	v_pk_add_f32 v[30:31], v[30:31], 1.0 op_sel_hi:[1,0]
	v_rcp_f32_e32 v28, v28
	v_rcp_f32_e32 v29, v29
	v_lshlrev_b64 v[158:159], 11, v[180:181]
	v_lshl_add_u64 v[158:159], s[72:73], 0, v[158:159]
	s_and_b64 vcc, exec, s[28:29]
	v_lshl_add_u64 v[158:159], v[198:199], 1, v[158:159]
	s_waitcnt vmcnt(3)
	v_lshlrev_b32_e32 v230, 16, v160
	v_and_b32_e32 v231, 0xffff0000, v160
	v_lshlrev_b32_e32 v160, 16, v161
	s_waitcnt vmcnt(3)
	v_lshlrev_b32_e32 v34, 16, v216
	v_and_b32_e32 v35, 0xffff0000, v216
	v_lshlrev_b32_e32 v196, 16, v217
	v_and_b32_e32 v197, 0xffff0000, v217
	v_rcp_f32_e32 v216, v30
	v_rcp_f32_e32 v217, v31
	v_and_b32_e32 v161, 0xffff0000, v161
	v_lshlrev_b32_e32 v30, 16, v218
	v_and_b32_e32 v31, 0xffff0000, v218
	v_lshlrev_b32_e32 v218, 16, v219
	v_and_b32_e32 v219, 0xffff0000, v219
	v_pk_fma_f32 v[32:33], v[32:33], v[196:197], v[160:161]
	v_lshlrev_b32_e32 v160, 16, v162
	v_and_b32_e32 v161, 0xffff0000, v162
	v_lshlrev_b32_e32 v162, 16, v163
	v_and_b32_e32 v163, 0xffff0000, v163
	v_pk_fma_f32 v[34:35], v[194:195], v[34:35], v[230:231]
	v_pk_fma_f32 v[30:31], v[28:29], v[30:31], v[160:161]
	v_pk_fma_f32 v[28:29], v[216:217], v[218:219], v[162:163]
	s_cbranch_vccz .LBB0_472
	v_cvt_pk_bf16_f32 v160, v34, v35
	v_cvt_pk_bf16_f32 v161, v32, v33
	v_cvt_pk_bf16_f32 v162, v30, v31
	v_cvt_pk_bf16_f32 v163, v28, v29
	global_store_dwordx4 v[158:159], v[160:163], off
.LBB0_472:
	v_mov_b32_e32 v157, v156
	s_nop 0
	v_mov_b32_e32 v160, v156
	v_mov_b32_e32 v161, v156
	v_pk_mul_f32 v[26:27], v[26:27], v[160:161]
	v_pk_mul_f32 v[24:25], v[24:25], v[156:157]
	v_pk_mul_f32 v[26:27], v[26:27], s[14:15] op_sel_hi:[1,0]
	v_pk_mul_f32 v[24:25], v[24:25], s[14:15] op_sel_hi:[1,0]
	v_pk_mul_f32 v[22:23], v[22:23], v[160:161]
	v_pk_mul_f32 v[20:21], v[20:21], v[156:157]
	v_exp_f32_e32 v24, v24
	v_exp_f32_e32 v26, v26
	v_exp_f32_e32 v27, v27
	v_exp_f32_e32 v25, v25
	v_pk_mul_f32 v[22:23], v[22:23], s[14:15] op_sel_hi:[1,0]
	v_pk_mul_f32 v[20:21], v[20:21], s[14:15] op_sel_hi:[1,0]
	v_exp_f32_e32 v22, v22
	v_exp_f32_e32 v20, v20
	v_exp_f32_e32 v23, v23
	v_exp_f32_e32 v21, v21
	v_pk_add_f32 v[26:27], v[26:27], 1.0 op_sel_hi:[1,0]
	v_pk_add_f32 v[24:25], v[24:25], 1.0 op_sel_hi:[1,0]
	v_rcp_f32_e32 v26, v26
	v_rcp_f32_e32 v24, v24
	v_rcp_f32_e32 v25, v25
	v_rcp_f32_e32 v27, v27
	v_pk_add_f32 v[22:23], v[22:23], 1.0 op_sel_hi:[1,0]
	v_pk_add_f32 v[20:21], v[20:21], 1.0 op_sel_hi:[1,0]
	v_rcp_f32_e32 v160, v22
	v_rcp_f32_e32 v156, v20
	v_rcp_f32_e32 v157, v21
	v_rcp_f32_e32 v161, v23
	s_waitcnt vmcnt(2)
	v_lshlrev_b32_e32 v162, 16, v56
	v_and_b32_e32 v163, 0xffff0000, v56
	v_lshlrev_b32_e32 v56, 16, v57
	v_and_b32_e32 v57, 0xffff0000, v57
	v_lshlrev_b32_e32 v22, 16, v52
	v_and_b32_e32 v23, 0xffff0000, v52
	v_lshlrev_b32_e32 v20, 16, v53
	v_and_b32_e32 v21, 0xffff0000, v53
	v_lshlrev_b32_e32 v194, 16, v58
	v_and_b32_e32 v195, 0xffff0000, v58
	v_lshlrev_b32_e32 v58, 16, v59
	v_and_b32_e32 v59, 0xffff0000, v59
	v_pk_fma_f32 v[20:21], v[26:27], v[56:57], v[20:21]
	v_pk_fma_f32 v[22:23], v[24:25], v[162:163], v[22:23]
	v_lshlrev_b32_e32 v24, 16, v54
	v_and_b32_e32 v25, 0xffff0000, v54
	v_lshlrev_b32_e32 v26, 16, v55
	v_and_b32_e32 v27, 0xffff0000, v55
	v_pk_fma_f32 v[24:25], v[156:157], v[194:195], v[24:25]
	v_pk_fma_f32 v[26:27], v[160:161], v[58:59], v[26:27]
	s_and_b64 vcc, exec, s[28:29]
	s_cbranch_vccz .LBB0_474
	v_cvt_pk_bf16_f32 v52, v22, v23
	v_cvt_pk_bf16_f32 v53, v20, v21
	v_cvt_pk_bf16_f32 v54, v24, v25
	v_cvt_pk_bf16_f32 v55, v26, v27
	global_store_dwordx4 v[158:159], v[52:55], off offset:256

.LBB0_476:
	s_or_b64 exec, exec, s[4:5]
	v_add_f32_e32 v52, v233, v234
	v_fmamk_f32 v52, v52, 0x3a800000, v226
	v_rsq_f32_e32 v52, v52
	s_waitcnt vmcnt(1)
	v_lshlrev_b32_e32 v56, 16, v48
	v_and_b32_e32 v57, 0xffff0000, v48
	v_lshlrev_b32_e32 v48, 16, v49
	s_waitcnt lgkmcnt(0)
	v_pk_mul_f32 v[16:17], v[16:17], v[52:53] op_sel_hi:[1,0]
	v_pk_mul_f32 v[18:19], v[18:19], v[52:53] op_sel_hi:[1,0]
	v_pk_mul_f32 v[16:17], v[16:17], s[14:15] op_sel_hi:[1,0]
	v_pk_mul_f32 v[18:19], v[18:19], s[14:15] op_sel_hi:[1,0]
	v_pk_mul_f32 v[12:13], v[12:13], v[52:53] op_sel_hi:[1,0]
	v_exp_f32_e32 v16, v16
	v_exp_f32_e32 v18, v18
	v_exp_f32_e32 v19, v19
	v_exp_f32_e32 v17, v17
	v_pk_mul_f32 v[14:15], v[14:15], v[52:53] op_sel_hi:[1,0]
	v_pk_mul_f32 v[12:13], v[12:13], s[14:15] op_sel_hi:[1,0]
	v_pk_mul_f32 v[14:15], v[14:15], s[14:15] op_sel_hi:[1,0]
	v_exp_f32_e32 v12, v12
	v_exp_f32_e32 v13, v13
	v_exp_f32_e32 v14, v14
	v_exp_f32_e32 v15, v15
	v_pk_add_f32 v[18:19], v[18:19], 1.0 op_sel_hi:[1,0]
	v_pk_add_f32 v[16:17], v[16:17], 1.0 op_sel_hi:[1,0]
	v_rcp_f32_e32 v18, v18
	v_rcp_f32_e32 v16, v16
	v_rcp_f32_e32 v17, v17
	v_rcp_f32_e32 v19, v19
	v_pk_add_f32 v[12:13], v[12:13], 1.0 op_sel_hi:[1,0]
	v_pk_add_f32 v[14:15], v[14:15], 1.0 op_sel_hi:[1,0]
	v_rcp_f32_e32 v12, v12
	v_rcp_f32_e32 v13, v13
	v_rcp_f32_e32 v14, v14
	v_rcp_f32_e32 v15, v15
	v_and_b32_e32 v49, 0xffff0000, v49
	v_lshlrev_b32_e32 v156, 16, v44
	v_and_b32_e32 v157, 0xffff0000, v44
	v_lshlrev_b32_e32 v44, 16, v45
	v_and_b32_e32 v45, 0xffff0000, v45
	v_lshlrev_b64 v[54:55], 11, v[178:179]
	v_lshlrev_b32_e32 v58, 16, v50
	v_and_b32_e32 v59, 0xffff0000, v50
	v_pk_fma_f32 v[44:45], v[18:19], v[48:49], v[44:45]
	v_pk_fma_f32 v[48:49], v[16:17], v[56:57], v[156:157]
	v_lshlrev_b32_e32 v16, 16, v46
	v_and_b32_e32 v17, 0xffff0000, v46
	v_lshlrev_b32_e32 v50, 16, v51
	v_and_b32_e32 v51, 0xffff0000, v51
	v_lshlrev_b32_e32 v18, 16, v47
	v_and_b32_e32 v19, 0xffff0000, v47
	v_pk_fma_f32 v[46:47], v[12:13], v[58:59], v[16:17]
	v_lshl_add_u64 v[12:13], s[72:73], 0, v[54:55]
	v_pk_fma_f32 v[50:51], v[14:15], v[50:51], v[18:19]
	s_and_b64 vcc, exec, s[28:29]
	v_lshl_add_u64 v[12:13], v[198:199], 1, v[12:13]
	s_cbranch_vccz .LBB0_478
	v_cvt_pk_bf16_f32 v14, v48, v49
	v_cvt_pk_bf16_f32 v15, v44, v45
	v_cvt_pk_bf16_f32 v16, v46, v47
	v_cvt_pk_bf16_f32 v17, v50, v51
	global_store_dwordx4 v[12:13], v[14:17], off

; __device__ __forceinline__ unsigned xb_ld(unsigned* p)              { return __hip_atomic_load(p, __ATOMIC_RELAXED, __HIP_MEMORY_SCOPE_AGENT); }
; __device__ __forceinline__ unsigned xb_add(unsigned* p, unsigned v) { return __hip_atomic_fetch_add(p, v, __ATOMIC_RELAXED, __HIP_MEMORY_SCOPE_AGENT); }
; #define XB_SPIN(cond, bar) do { unsigned _sp = 0; while (cond) { __builtin_amdgcn_s_sleep(1); \
;     if ((++_sp & 255u) == 0u) { if (xb_ld(&(bar)[XB_TMO])) break; if (_sp > XB_SPIN_CAP) { atomicAdd(&(bar)[XB_TMO], 1u); break; } } } } while (0)
; __device__ __forceinline__ void xcd_barrier_thread0(const XcdBarrier& b) {
;     ...
;         const unsigned old = xb_add(&bar[XB_XSUB(b.x)], 1u);
;         const unsigned gen = old / nloc;
;         if (old + 1u == (gen + 1u) * nloc) {
;             __builtin_amdgcn_fence(__ATOMIC_RELEASE, "agent");
;             asm volatile("s_waitcnt vmcnt(0)" ::: "memory");
;             const unsigned og = xb_add(&bar[XB_TOP], 1u);
;             const unsigned tg = og / nx;
;             if (og + 1u == (tg + 1u) * nx) xb_add(&bar[XB_TOPGEN], 1u);
;             else XB_SPIN(xb_ld(&bar[XB_TOPGEN]) == tg, bar);
;             __builtin_amdgcn_fence(__ATOMIC_ACQUIRE, "agent");
;             xb_add(&bar[XB_XGEN(b.x)], 1u);
;             asm volatile("s_waitcnt vmcnt(0)" ::: "memory");
;         } else {
;             XB_SPIN(xb_ld(&bar[XB_XGEN(b.x)]) == gen, bar);
.LBB0_501:
	s_or_b64 exec, exec, s[0:1]
	v_cvt_f32_u32_e32 v9, v7
	s_waitcnt vmcnt(0)
	v_readfirstlane_b32 s0, v8
	v_sub_u32_e32 v8, 0, v7
	v_rcp_iflag_f32_e32 v9, v9
	v_add_u32_e32 v10, s0, v5
	v_mul_f32_e32 v9, 0x4f7ffffe, v9
	v_cvt_u32_f32_e32 v9, v9
	v_mul_lo_u32 v5, v8, v9
	v_mul_hi_u32 v5, v9, v5
	v_add_u32_e32 v5, v9, v5
	v_mul_hi_u32 v5, v10, v5
	v_mul_lo_u32 v8, v5, v7
	v_sub_u32_e32 v8, v10, v8
	v_add_u32_e32 v9, 1, v5
	v_cmp_ge_u32_e32 vcc, v8, v7
	s_nop 1
	v_cndmask_b32_e32 v5, v5, v9, vcc
	v_sub_u32_e32 v9, v8, v7
	v_cndmask_b32_e32 v8, v8, v9, vcc
	v_add_u32_e32 v9, 1, v5
	v_cmp_ge_u32_e32 vcc, v8, v7
	v_add_u32_e32 v8, 1, v10
	s_nop 0
	v_cndmask_b32_e32 v5, v5, v9, vcc
	v_mul_lo_u32 v9, v7, v5
	v_add_u32_e32 v7, v9, v7
	v_cmp_ne_u32_e32 vcc, v8, v7
	s_and_saveexec_b64 s[0:1], vcc
	s_xor_b64 s[0:1], exec, s[0:1]
	s_cbranch_execz .LBB0_515
	v_readlane_b32 s6, v253, 14
	v_readlane_b32 s7, v253, 15
	s_waitcnt lgkmcnt(0)
	s_nop 3
	buffer_inv sc1
	global_load_dword v4, v3, s[6:7] sc1
	s_waitcnt vmcnt(0)
	v_cmp_eq_u32_e32 vcc, v4, v5
	s_and_saveexec_b64 s[6:7], vcc
	s_cbranch_execz .LBB0_514
	s_mov_b32 s15, 1
	s_mov_b64 s[8:9], 0
	s_branch .LBB0_505

; __device__ __forceinline__ unsigned xb_ld(unsigned* p)              { return __hip_atomic_load(p, __ATOMIC_RELAXED, __HIP_MEMORY_SCOPE_AGENT); }
; #define XB_SPIN(cond, bar) do { unsigned _sp = 0; while (cond) { __builtin_amdgcn_s_sleep(1); \
;     if ((++_sp & 255u) == 0u) { if (xb_ld(&(bar)[XB_TMO])) break; if (_sp > XB_SPIN_CAP) { atomicAdd(&(bar)[XB_TMO], 1u); break; } } } } while (0)
; __device__ __forceinline__ void xcd_barrier_thread0(const XcdBarrier& b) {
;     ...
;             XB_SPIN(xb_ld(&bar[XB_XGEN(b.x)]) == gen, bar);
.LBB0_507:
	v_readlane_b32 s16, v253, 14
	v_readlane_b32 s17, v253, 15
	s_add_i32 s15, s15, 1
	s_mov_b64 s[20:21], -1
	s_nop 2
	global_load_dword v4, v3, s[16:17] sc1
	s_waitcnt vmcnt(0)
	v_cmp_ne_u32_e32 vcc, v4, v5
	s_orn2_b64 s[16:17], vcc, exec
	s_branch .LBB0_504

; __device__ __forceinline__ unsigned xb_ld(unsigned* p)              { return __hip_atomic_load(p, __ATOMIC_RELAXED, __HIP_MEMORY_SCOPE_AGENT); }
; __device__ __forceinline__ unsigned xb_add(unsigned* p, unsigned v) { return __hip_atomic_fetch_add(p, v, __ATOMIC_RELAXED, __HIP_MEMORY_SCOPE_AGENT); }
; #define XB_SPIN(cond, bar) do { unsigned _sp = 0; while (cond) { __builtin_amdgcn_s_sleep(1); \
;     if ((++_sp & 255u) == 0u) { if (xb_ld(&(bar)[XB_TMO])) break; if (_sp > XB_SPIN_CAP) { atomicAdd(&(bar)[XB_TMO], 1u); break; } } } } while (0)
; __device__ __forceinline__ void xcd_barrier_thread0(const XcdBarrier& b) {
;     ...
;         const unsigned old = xb_add(&bar[XB_XSUB(b.x)], 1u);
;         const unsigned gen = old / nloc;
;         if (old + 1u == (gen + 1u) * nloc) {
;             __builtin_amdgcn_fence(__ATOMIC_RELEASE, "agent");
;             asm volatile("s_waitcnt vmcnt(0)" ::: "memory");
;             const unsigned og = xb_add(&bar[XB_TOP], 1u);
;             const unsigned tg = og / nx;
;             if (og + 1u == (tg + 1u) * nx) xb_add(&bar[XB_TOPGEN], 1u);
;             else XB_SPIN(xb_ld(&bar[XB_TOPGEN]) == tg, bar);
;             __builtin_amdgcn_fence(__ATOMIC_ACQUIRE, "agent");
;             xb_add(&bar[XB_XGEN(b.x)], 1u);
;             asm volatile("s_waitcnt vmcnt(0)" ::: "memory");
;         } else {
;             XB_SPIN(xb_ld(&bar[XB_XGEN(b.x)]) == gen, bar);
.LBB0_721:
	s_or_b64 exec, exec, s[0:1]
	v_cvt_f32_u32_e32 v7, v5
	s_waitcnt vmcnt(0)
	v_readfirstlane_b32 s0, v6
	v_sub_u32_e32 v6, 0, v5
	v_rcp_iflag_f32_e32 v7, v7
	v_add_u32_e32 v8, s0, v2
	v_mul_f32_e32 v7, 0x4f7ffffe, v7
	v_cvt_u32_f32_e32 v7, v7
	v_mul_lo_u32 v2, v6, v7
	v_mul_hi_u32 v2, v7, v2
	v_add_u32_e32 v2, v7, v2
	v_mul_hi_u32 v2, v8, v2
	v_mul_lo_u32 v6, v2, v5
	v_sub_u32_e32 v6, v8, v6
	v_add_u32_e32 v7, 1, v2
	v_cmp_ge_u32_e32 vcc, v6, v5
	s_nop 1
	v_cndmask_b32_e32 v2, v2, v7, vcc
	v_sub_u32_e32 v7, v6, v5
	v_cndmask_b32_e32 v6, v6, v7, vcc
	v_add_u32_e32 v7, 1, v2
	v_cmp_ge_u32_e32 vcc, v6, v5
	v_add_u32_e32 v6, 1, v8
	s_nop 0
	v_cndmask_b32_e32 v2, v2, v7, vcc
	v_mul_lo_u32 v7, v5, v2
	v_add_u32_e32 v5, v7, v5
	v_cmp_ne_u32_e32 vcc, v6, v5
	s_and_saveexec_b64 s[0:1], vcc
	s_xor_b64 s[0:1], exec, s[0:1]
	s_cbranch_execz .LBB0_735
	v_readlane_b32 s8, v253, 14
	v_readlane_b32 s9, v253, 15
	s_waitcnt lgkmcnt(0)
	s_nop 3
	buffer_inv sc1
	global_load_dword v4, v3, s[8:9] sc1
	s_waitcnt vmcnt(0)
	v_cmp_eq_u32_e32 vcc, v4, v2
	s_and_saveexec_b64 s[8:9], vcc
	s_cbranch_execz .LBB0_734
	s_mov_b32 s15, 1
	s_mov_b64 s[12:13], 0
	s_branch .LBB0_725

; #define LAS __attribute__((address_space(3)))
; __device__ __forceinline__ void cv_background(Frame& F, const CvPtrs& P, int s) {
;     int tv = threadIdx.x; asm volatile("" : "+v"(tv));
;     const int w = __builtin_amdgcn_readfirstlane(tv >> 6) - 1, lane = tv & 63, nbw = F.G * (NWAVES - 1);
;     LAS float* scr = (LAS float*)(F.lds + RING_OFF + (w + 1) * 16384);
;     const int sh_ = cv_bg_share(s), hi = (sh_ + 1) * CV_BG_PER < CV_BG_TOTAL ? (sh_ + 1) * CV_BG_PER : CV_BG_TOTAL;
;     for (int j = sh_ * CV_BG_PER + F.vcu * (NWAVES - 1) + w; j < hi; j += nbw) {
; __device__ __forceinline__ void xcd_barrier_cv(const XcdBarrier& b, Frame& F, const CvPtrs& P, int s, bool local) {
;     ...
;     else if (cv_bg_share(s) >= 0 && cv_bg_share(s) < CV_BG_SHARES) cv_background(F, P, s);
.LBB0_769:
	s_and_b64 vcc, exec, s[0:1]
	s_cbranch_vccz .LBB0_1015
	s_sleep 100
	v_mov_b32_e32 v4, v0
	s_mov_b64 s[6:7], -1
	v_readfirstlane_b32 s8, v4
	s_mov_b64 s[0:1], 0
	s_cmp_lt_i32 s89, 5
	s_mov_b64 s[4:5], 0
	s_cbranch_scc1 .LBB0_787
	s_cmp_gt_i32 s89, 7
	s_cbranch_scc0 .LBB0_779
	s_cmp_gt_i32 s89, 8
	s_cbranch_scc0 .LBB0_776
	s_cmp_eq_u32 s89, 9
	s_mov_b64 s[4:5], -1
	s_cbranch_scc0 .LBB0_775
	s_mov_b64 s[4:5], 0

; __device__ __forceinline__ unsigned xb_ld(unsigned* p)              { return __hip_atomic_load(p, __ATOMIC_RELAXED, __HIP_MEMORY_SCOPE_AGENT); }
; __device__ __forceinline__ unsigned xb_add(unsigned* p, unsigned v) { return __hip_atomic_fetch_add(p, v, __ATOMIC_RELAXED, __HIP_MEMORY_SCOPE_AGENT); }
; #define XB_SPIN(cond, bar) do { unsigned _sp = 0; while (cond) { __builtin_amdgcn_s_sleep(1); \
;     if ((++_sp & 255u) == 0u) { if (xb_ld(&(bar)[XB_TMO])) break; if (_sp > XB_SPIN_CAP) { atomicAdd(&(bar)[XB_TMO], 1u); break; } } } } while (0)
; __device__ __forceinline__ void xcd_barrier_thread0(const XcdBarrier& b) {
;     ...
;         const unsigned old = xb_add(&bar[XB_XSUB(b.x)], 1u);
;         const unsigned gen = old / nloc;
;         if (old + 1u == (gen + 1u) * nloc) {
;             __builtin_amdgcn_fence(__ATOMIC_RELEASE, "agent");
;             asm volatile("s_waitcnt vmcnt(0)" ::: "memory");
;             const unsigned og = xb_add(&bar[XB_TOP], 1u);
;             const unsigned tg = og / nx;
;             if (og + 1u == (tg + 1u) * nx) xb_add(&bar[XB_TOPGEN], 1u);
;             else XB_SPIN(xb_ld(&bar[XB_TOPGEN]) == tg, bar);
;             __builtin_amdgcn_fence(__ATOMIC_ACQUIRE, "agent");
;             xb_add(&bar[XB_XGEN(b.x)], 1u);
;             asm volatile("s_waitcnt vmcnt(0)" ::: "memory");
;         } else {
;             XB_SPIN(xb_ld(&bar[XB_XGEN(b.x)]) == gen, bar);
.LBB0_1036:
	s_or_b64 exec, exec, s[0:1]
	v_cvt_f32_u32_e32 v8, v6
	s_waitcnt vmcnt(0)
	v_readfirstlane_b32 s0, v7
	v_sub_u32_e32 v7, 0, v6
	v_rcp_iflag_f32_e32 v8, v8
	v_add_u32_e32 v9, s0, v5
	v_mul_f32_e32 v8, 0x4f7ffffe, v8
	v_cvt_u32_f32_e32 v8, v8
	v_mul_lo_u32 v5, v7, v8
	v_mul_hi_u32 v5, v8, v5
	v_add_u32_e32 v5, v8, v5
	v_mul_hi_u32 v5, v9, v5
	v_mul_lo_u32 v7, v5, v6
	v_sub_u32_e32 v7, v9, v7
	v_add_u32_e32 v8, 1, v5
	v_cmp_ge_u32_e32 vcc, v7, v6
	s_nop 1
	v_cndmask_b32_e32 v5, v5, v8, vcc
	v_sub_u32_e32 v8, v7, v6
	v_cndmask_b32_e32 v7, v7, v8, vcc
	v_add_u32_e32 v8, 1, v5
	v_cmp_ge_u32_e32 vcc, v7, v6
	v_add_u32_e32 v7, 1, v9
	s_nop 0
	v_cndmask_b32_e32 v5, v5, v8, vcc
	v_mul_lo_u32 v8, v6, v5
	v_add_u32_e32 v6, v8, v6
	v_cmp_ne_u32_e32 vcc, v7, v6
	s_and_saveexec_b64 s[0:1], vcc
	s_xor_b64 s[0:1], exec, s[0:1]
	s_cbranch_execz .LBB0_1050
	v_readlane_b32 s2, v253, 14
	v_readlane_b32 s3, v253, 15
	s_waitcnt lgkmcnt(0)
	s_nop 3
	buffer_inv sc1
	global_load_dword v4, v3, s[2:3] sc1
	s_waitcnt vmcnt(0)
	v_cmp_eq_u32_e32 vcc, v4, v5
	s_and_saveexec_b64 s[2:3], vcc
	s_cbranch_execz .LBB0_1049
	s_mov_b32 s15, 1
	s_mov_b64 s[8:9], 0
	s_branch .LBB0_1040

; __device__ __forceinline__ unsigned xb_ld(unsigned* p)              { return __hip_atomic_load(p, __ATOMIC_RELAXED, __HIP_MEMORY_SCOPE_AGENT); }
; #define XB_SPIN(cond, bar) do { unsigned _sp = 0; while (cond) { __builtin_amdgcn_s_sleep(1); \
;     if ((++_sp & 255u) == 0u) { if (xb_ld(&(bar)[XB_TMO])) break; if (_sp > XB_SPIN_CAP) { atomicAdd(&(bar)[XB_TMO], 1u); break; } } } } while (0)
; __device__ __forceinline__ void xcd_barrier_thread0(const XcdBarrier& b) {
;     ...
;             XB_SPIN(xb_ld(&bar[XB_XGEN(b.x)]) == gen, bar);
.LBB0_1042:
	v_readlane_b32 s16, v253, 14
	v_readlane_b32 s17, v253, 15
	s_add_i32 s15, s15, 1
	s_mov_b64 s[18:19], -1
	s_nop 2
	global_load_dword v4, v3, s[16:17] sc1
	s_waitcnt vmcnt(0)
	v_cmp_ne_u32_e32 vcc, v4, v5
	s_orn2_b64 s[16:17], vcc, exec
	s_branch .LBB0_1039
